# v106 with the stagger groups swapped: waves 0-3 take the end-of-tile barrier, waves 4-7 the mid-tile one
# speedup vs baseline: 1.0072x; 1.0014x over previous
.Lmla_fast:
	s_mov_b32 s42, s30
	s_and_b32 s8, s30, 3
	s_mulk_i32 s8, 0x6400
	s_add_i32 s8, s8, 0
	v_add3_u32 v142, s8, v144, v145
	v_add3_u32 v0, s8, v143, v132
	ds_read_b128 v[194:197], v0
	ds_read_b128 v[150:153], v0 offset:32
	ds_read_b128 v[158:161], v0 offset:64
	ds_read_b128 v[162:165], v0 offset:96
	ds_read_b128 v[174:177], v0 offset:128
	ds_read_b128 v[178:181], v0 offset:160
	s_cmp_ge_u32 s5, 0x1000
	s_cbranch_scc1 .Lmla_fast_grpA
	s_bitcmp1_b32 s30, 0
	s_cbranch_scc1 .Lmla_fast_havek_oB
	s_branch .Lmla_fast_havek_eB
